# in-proj and gate/up epilogues, rstd-cache-miss path: the 8 row groups' ssq loads issued together at the first group, counted vmcnt(7) per group instead of load+vmcnt(0) per group
# speedup vs baseline: 1.0095x; 1.0047x over previous
; #define LAS __attribute__((address_space(3)))
; __device__ __forceinline__ float row_rstd(const float* ssq, int row, int fq) {
;     const f32x4 s = *(const f32x4*)(ssq + (size_t)row * 16 + 4 * fq);
;     float t = (s[0] + s[1]) + (s[2] + s[3]);
;     t += __shfl_xor(t, 16); t += __shfl_xor(t, 32);
;     return rsqrtf(t * (1.0f / DM) + EPS);
; }
; __device__ __forceinline__ bool rc_hit(LAS float* rc, const int want, const int wave) { return __builtin_amdgcn_readfirstlane(*(volatile LAS int*)((LAS int*)(rc + 1024) + wave)) == want; }
; __device__ __forceinline__ float rc_get(LAS float* rc, const bool hit, const float* ssq, const int row, const int wave, const int slot, const int fr, const int fq) {
;     LAS float* e = rc + wave * 128 + slot * 16 + fr;
;     if (hit) return *e;
;     const float r = row_rstd(ssq, row, fq); if (fq == 0) *e = r; return r;
;     __device__ __forceinline__ void operator()(const f32x4 (&acc)[2][2][4][2], const pg8::Unit& u, int wr, int wc, int fr, int fq) const {
;     ...
;         for (int ai = 0; ai < 2; ++ai)
; #pragma unroll
;             for (int m = 0; m < 4; ++m) {
;                 const int row = row0 + ai * 128 + m * 16; const float rs = rc_get(rc, rchit, ssq, row, rcw, ai * 4 + m, fr, fq);
.LBB0_603:
	s_lshl_b32 s4, s36, 8
	s_add_i32 s27, s51, s36
	s_cmp_lg_u32 s29, s27
	s_cselect_b64 s[36:37], -1, 0
	s_add_i32 s4, s4, s47
	v_add_u32_e32 v166, s4, v164
	v_lshl_add_u32 v205, v164, 2, s53
	v_ashrrev_i32_e32 v167, 31, v166
	s_mov_b64 s[12:13], -1
	s_and_b64 vcc, exec, s[36:37]
	s_cbranch_vccz .LBB0_607
	v_lshlrev_b64 v[164:165], 6, v[166:167]
	v_lshl_add_u64 v[164:165], v[158:159], 0, v[164:165]
	s_mov_b32 s100, 0x2000
	s_mov_b32 s101, 0
	v_lshl_add_u64 v[240:241], v[164:165], 0, s[100:101]
	global_load_dwordx4 v[208:211], v[164:165], off
	global_load_dwordx4 v[212:215], v[164:165], off offset:1024
	global_load_dwordx4 v[216:219], v[164:165], off offset:2048
	global_load_dwordx4 v[220:223], v[164:165], off offset:3072
	global_load_dwordx4 v[224:227], v[240:241], off
	global_load_dwordx4 v[228:231], v[240:241], off offset:1024
	global_load_dwordx4 v[232:235], v[240:241], off offset:2048
	global_load_dwordx4 v[236:239], v[240:241], off offset:3072
	s_waitcnt vmcnt(7)
	v_mov_b32_e32 v168, v208
	v_mov_b32_e32 v169, v209
	v_mov_b32_e32 v170, v210
	v_mov_b32_e32 v171, v211
	v_mov_b32_e32 v164, v169
	v_mov_b32_e32 v165, v170
	v_mov_b32_e32 v169, v171
	v_pk_add_f32 v[164:165], v[164:165], v[168:169]
	s_nop 0
	v_add_f32_e32 v164, v164, v165
	ds_bpermute_b32 v165, v131, v164
	s_waitcnt lgkmcnt(0)
	v_add_f32_e32 v164, v164, v165
	ds_bpermute_b32 v165, v135, v164
	s_waitcnt lgkmcnt(0)
	v_add_f32_e32 v164, v164, v165
	v_fmamk_f32 v164, v164, 0x3a800000, v195
	v_mul_f32_e32 v165, 0x4b800000, v164
	v_cmp_gt_f32_e32 vcc, s68, v164
	s_nop 1
	v_cndmask_b32_e32 v164, v164, v165, vcc
	v_rsq_f32_e32 v164, v164
	s_nop 0
	v_mul_f32_e32 v165, 0x45800000, v164
	v_cndmask_b32_e32 v168, v164, v165, vcc
	s_and_saveexec_b64 s[12:13], s[6:7]
	ds_write_b32 v205, v168
	s_or_b64 exec, exec, s[12:13]
	s_mov_b64 s[12:13], 0

; #define LAS __attribute__((address_space(3)))
; __device__ __forceinline__ float row_rstd(const float* ssq, int row, int fq) {
;     const f32x4 s = *(const f32x4*)(ssq + (size_t)row * 16 + 4 * fq);
;     float t = (s[0] + s[1]) + (s[2] + s[3]);
;     t += __shfl_xor(t, 16); t += __shfl_xor(t, 32);
;     return rsqrtf(t * (1.0f / DM) + EPS);
; }
; __device__ __forceinline__ bool rc_hit(LAS float* rc, const int want, const int wave) { return __builtin_amdgcn_readfirstlane(*(volatile LAS int*)((LAS int*)(rc + 1024) + wave)) == want; }
; __device__ __forceinline__ float rc_get(LAS float* rc, const bool hit, const float* ssq, const int row, const int wave, const int slot, const int fr, const int fq) {
;     LAS float* e = rc + wave * 128 + slot * 16 + fr;
;     if (hit) return *e;
;     const float r = row_rstd(ssq, row, fq); if (fq == 0) *e = r; return r;
.LBB0_628:
	s_nop 1
	v_add_u32_e32 v116, 16, v166
	v_cndmask_b32_e64 v114, 0, 1, s[36:37]
	v_ashrrev_i32_e32 v117, 31, v116
	v_cmp_ne_u32_e64 s[12:13], 1, v114
	s_andn2_b64 vcc, exec, s[36:37]
	s_mov_b64 s[14:15], -1
	s_cbranch_vccnz .LBB0_632
	v_lshlrev_b64 v[114:115], 6, v[116:117]
	v_lshl_add_u64 v[114:115], v[158:159], 0, v[114:115]
	s_waitcnt vmcnt(7)
	v_mov_b32_e32 v118, v212
	v_mov_b32_e32 v119, v213
	v_mov_b32_e32 v120, v214
	v_mov_b32_e32 v121, v215
	v_mov_b32_e32 v114, v119
	v_mov_b32_e32 v115, v120
	v_mov_b32_e32 v119, v121
	v_pk_add_f32 v[114:115], v[114:115], v[118:119]
	s_nop 0
	v_add_f32_e32 v114, v114, v115
	ds_bpermute_b32 v115, v131, v114
	s_waitcnt lgkmcnt(0)
	v_add_f32_e32 v114, v114, v115
	ds_bpermute_b32 v115, v135, v114
	s_waitcnt lgkmcnt(0)
	v_add_f32_e32 v114, v114, v115
	v_fmamk_f32 v114, v114, 0x3a800000, v195
	v_mul_f32_e32 v115, 0x4b800000, v114
	v_cmp_gt_f32_e32 vcc, s68, v114
	s_nop 1
	v_cndmask_b32_e32 v114, v114, v115, vcc
	v_rsq_f32_e32 v114, v114
	s_nop 0
	v_mul_f32_e32 v115, 0x45800000, v114
	v_cndmask_b32_e32 v114, v114, v115, vcc
	s_and_saveexec_b64 s[14:15], s[6:7]
	ds_write_b32 v205, v114 offset:64
	s_or_b64 exec, exec, s[14:15]
	s_mov_b64 s[14:15], 0

; #define LAS __attribute__((address_space(3)))
; __device__ __forceinline__ float row_rstd(const float* ssq, int row, int fq) {
;     const f32x4 s = *(const f32x4*)(ssq + (size_t)row * 16 + 4 * fq);
;     float t = (s[0] + s[1]) + (s[2] + s[3]);
;     t += __shfl_xor(t, 16); t += __shfl_xor(t, 32);
;     return rsqrtf(t * (1.0f / DM) + EPS);
; }
; __device__ __forceinline__ bool rc_hit(LAS float* rc, const int want, const int wave) { return __builtin_amdgcn_readfirstlane(*(volatile LAS int*)((LAS int*)(rc + 1024) + wave)) == want; }
; __device__ __forceinline__ float rc_get(LAS float* rc, const bool hit, const float* ssq, const int row, const int wave, const int slot, const int fr, const int fq) {
;     LAS float* e = rc + wave * 128 + slot * 16 + fr;
;     if (hit) return *e;
;     const float r = row_rstd(ssq, row, fq); if (fq == 0) *e = r; return r;
.LBB0_653:
	s_nop 1
	v_add_u32_e32 v100, 32, v166
	v_ashrrev_i32_e32 v101, 31, v100
	s_and_b64 vcc, exec, s[12:13]
	s_mov_b64 s[38:39], -1
	s_cbranch_vccnz .LBB0_657
	v_lshlrev_b64 v[98:99], 6, v[100:101]
	v_lshl_add_u64 v[98:99], v[158:159], 0, v[98:99]
	s_waitcnt vmcnt(7)
	v_mov_b32_e32 v102, v216
	v_mov_b32_e32 v103, v217
	v_mov_b32_e32 v104, v218
	v_mov_b32_e32 v105, v219
	v_mov_b32_e32 v98, v103
	v_mov_b32_e32 v99, v104
	v_mov_b32_e32 v103, v105
	v_pk_add_f32 v[98:99], v[98:99], v[102:103]
	s_nop 0
	v_add_f32_e32 v98, v98, v99
	ds_bpermute_b32 v99, v131, v98
	s_waitcnt lgkmcnt(0)
	v_add_f32_e32 v98, v98, v99
	ds_bpermute_b32 v99, v135, v98
	s_waitcnt lgkmcnt(0)
	v_add_f32_e32 v98, v98, v99
	v_fmamk_f32 v98, v98, 0x3a800000, v195
	v_mul_f32_e32 v99, 0x4b800000, v98
	v_cmp_gt_f32_e32 vcc, s68, v98
	s_nop 1
	v_cndmask_b32_e32 v98, v98, v99, vcc
	v_rsq_f32_e32 v98, v98
	s_nop 0
	v_mul_f32_e32 v99, 0x45800000, v98
	v_cndmask_b32_e32 v98, v98, v99, vcc
	s_and_saveexec_b64 s[38:39], s[6:7]
	ds_write_b32 v205, v98 offset:128
	s_or_b64 exec, exec, s[38:39]
	s_mov_b64 s[38:39], 0

; #define LAS __attribute__((address_space(3)))
; __device__ __forceinline__ float row_rstd(const float* ssq, int row, int fq) {
;     const f32x4 s = *(const f32x4*)(ssq + (size_t)row * 16 + 4 * fq);
;     float t = (s[0] + s[1]) + (s[2] + s[3]);
;     t += __shfl_xor(t, 16); t += __shfl_xor(t, 32);
;     return rsqrtf(t * (1.0f / DM) + EPS);
; }
; __device__ __forceinline__ bool rc_hit(LAS float* rc, const int want, const int wave) { return __builtin_amdgcn_readfirstlane(*(volatile LAS int*)((LAS int*)(rc + 1024) + wave)) == want; }
; __device__ __forceinline__ float rc_get(LAS float* rc, const bool hit, const float* ssq, const int row, const int wave, const int slot, const int fr, const int fq) {
;     LAS float* e = rc + wave * 128 + slot * 16 + fr;
;     if (hit) return *e;
;     const float r = row_rstd(ssq, row, fq); if (fq == 0) *e = r; return r;
.LBB0_678:
	s_nop 1
	v_add_u32_e32 v84, 48, v166
	v_ashrrev_i32_e32 v85, 31, v84
	s_and_b64 vcc, exec, s[12:13]
	s_mov_b64 s[38:39], -1
	s_cbranch_vccnz .LBB0_682
	v_lshlrev_b64 v[82:83], 6, v[84:85]
	v_lshl_add_u64 v[82:83], v[158:159], 0, v[82:83]
	s_waitcnt vmcnt(7)
	v_mov_b32_e32 v86, v220
	v_mov_b32_e32 v87, v221
	v_mov_b32_e32 v88, v222
	v_mov_b32_e32 v89, v223
	v_mov_b32_e32 v82, v87
	v_mov_b32_e32 v83, v88
	v_mov_b32_e32 v87, v89
	v_pk_add_f32 v[82:83], v[82:83], v[86:87]
	s_nop 0
	v_add_f32_e32 v82, v82, v83
	ds_bpermute_b32 v83, v131, v82
	s_waitcnt lgkmcnt(0)
	v_add_f32_e32 v82, v82, v83
	ds_bpermute_b32 v83, v135, v82
	s_waitcnt lgkmcnt(0)
	v_add_f32_e32 v82, v82, v83
	v_fmamk_f32 v82, v82, 0x3a800000, v195
	v_mul_f32_e32 v83, 0x4b800000, v82
	v_cmp_gt_f32_e32 vcc, s68, v82
	s_nop 1
	v_cndmask_b32_e32 v82, v82, v83, vcc
	v_rsq_f32_e32 v82, v82
	s_nop 0
	v_mul_f32_e32 v83, 0x45800000, v82
	v_cndmask_b32_e32 v82, v82, v83, vcc
	s_and_saveexec_b64 s[38:39], s[6:7]
	ds_write_b32 v205, v82 offset:192
	s_or_b64 exec, exec, s[38:39]
	s_mov_b64 s[38:39], 0

; #define LAS __attribute__((address_space(3)))
; __device__ __forceinline__ float row_rstd(const float* ssq, int row, int fq) {
;     const f32x4 s = *(const f32x4*)(ssq + (size_t)row * 16 + 4 * fq);
;     float t = (s[0] + s[1]) + (s[2] + s[3]);
;     t += __shfl_xor(t, 16); t += __shfl_xor(t, 32);
;     return rsqrtf(t * (1.0f / DM) + EPS);
; }
; __device__ __forceinline__ bool rc_hit(LAS float* rc, const int want, const int wave) { return __builtin_amdgcn_readfirstlane(*(volatile LAS int*)((LAS int*)(rc + 1024) + wave)) == want; }
; __device__ __forceinline__ float rc_get(LAS float* rc, const bool hit, const float* ssq, const int row, const int wave, const int slot, const int fr, const int fq) {
;     LAS float* e = rc + wave * 128 + slot * 16 + fr;
;     if (hit) return *e;
;     const float r = row_rstd(ssq, row, fq); if (fq == 0) *e = r; return r;
.LBB0_703:
	s_nop 1
	v_add_u32_e32 v68, 0x80, v166
	v_ashrrev_i32_e32 v69, 31, v68
	s_and_b64 vcc, exec, s[12:13]
	s_mov_b64 s[38:39], -1
	s_cbranch_vccnz .LBB0_707
	v_lshlrev_b64 v[66:67], 6, v[68:69]
	v_lshl_add_u64 v[66:67], v[158:159], 0, v[66:67]
	s_waitcnt vmcnt(7)
	v_mov_b32_e32 v70, v224
	v_mov_b32_e32 v71, v225
	v_mov_b32_e32 v72, v226
	v_mov_b32_e32 v73, v227
	v_mov_b32_e32 v66, v71
	v_mov_b32_e32 v67, v72
	v_mov_b32_e32 v71, v73
	v_pk_add_f32 v[66:67], v[66:67], v[70:71]
	s_nop 0
	v_add_f32_e32 v66, v66, v67
	ds_bpermute_b32 v67, v131, v66
	s_waitcnt lgkmcnt(0)
	v_add_f32_e32 v66, v66, v67
	ds_bpermute_b32 v67, v135, v66
	s_waitcnt lgkmcnt(0)
	v_add_f32_e32 v66, v66, v67
	v_fmamk_f32 v66, v66, 0x3a800000, v195
	v_mul_f32_e32 v67, 0x4b800000, v66
	v_cmp_gt_f32_e32 vcc, s68, v66
	s_nop 1
	v_cndmask_b32_e32 v66, v66, v67, vcc
	v_rsq_f32_e32 v66, v66
	s_nop 0
	v_mul_f32_e32 v67, 0x45800000, v66
	v_cndmask_b32_e32 v66, v66, v67, vcc
	s_and_saveexec_b64 s[38:39], s[6:7]
	ds_write_b32 v205, v66 offset:256
	s_or_b64 exec, exec, s[38:39]
	s_mov_b64 s[38:39], 0

; #define LAS __attribute__((address_space(3)))
; __device__ __forceinline__ float row_rstd(const float* ssq, int row, int fq) {
;     const f32x4 s = *(const f32x4*)(ssq + (size_t)row * 16 + 4 * fq);
;     float t = (s[0] + s[1]) + (s[2] + s[3]);
;     t += __shfl_xor(t, 16); t += __shfl_xor(t, 32);
;     return rsqrtf(t * (1.0f / DM) + EPS);
; }
; __device__ __forceinline__ bool rc_hit(LAS float* rc, const int want, const int wave) { return __builtin_amdgcn_readfirstlane(*(volatile LAS int*)((LAS int*)(rc + 1024) + wave)) == want; }
; __device__ __forceinline__ float rc_get(LAS float* rc, const bool hit, const float* ssq, const int row, const int wave, const int slot, const int fr, const int fq) {
;     LAS float* e = rc + wave * 128 + slot * 16 + fr;
;     if (hit) return *e;
;     const float r = row_rstd(ssq, row, fq); if (fq == 0) *e = r; return r;
.LBB0_728:
	s_nop 1
	v_add_u32_e32 v52, 0x90, v166
	v_ashrrev_i32_e32 v53, 31, v52
	s_and_b64 vcc, exec, s[12:13]
	s_mov_b64 s[38:39], -1
	s_cbranch_vccnz .LBB0_732
	v_lshlrev_b64 v[50:51], 6, v[52:53]
	v_lshl_add_u64 v[50:51], v[158:159], 0, v[50:51]
	s_waitcnt vmcnt(7)
	v_mov_b32_e32 v54, v228
	v_mov_b32_e32 v55, v229
	v_mov_b32_e32 v56, v230
	v_mov_b32_e32 v57, v231
	v_mov_b32_e32 v50, v55
	v_mov_b32_e32 v51, v56
	v_mov_b32_e32 v55, v57
	v_pk_add_f32 v[50:51], v[50:51], v[54:55]
	s_nop 0
	v_add_f32_e32 v50, v50, v51
	ds_bpermute_b32 v51, v131, v50
	s_waitcnt lgkmcnt(0)
	v_add_f32_e32 v50, v50, v51
	ds_bpermute_b32 v51, v135, v50
	s_waitcnt lgkmcnt(0)
	v_add_f32_e32 v50, v50, v51
	v_fmamk_f32 v50, v50, 0x3a800000, v195
	v_mul_f32_e32 v51, 0x4b800000, v50
	v_cmp_gt_f32_e32 vcc, s68, v50
	s_nop 1
	v_cndmask_b32_e32 v50, v50, v51, vcc
	v_rsq_f32_e32 v50, v50
	s_nop 0
	v_mul_f32_e32 v51, 0x45800000, v50
	v_cndmask_b32_e32 v50, v50, v51, vcc
	s_and_saveexec_b64 s[38:39], s[6:7]
	ds_write_b32 v205, v50 offset:320
	s_or_b64 exec, exec, s[38:39]
	s_mov_b64 s[38:39], 0

; #define LAS __attribute__((address_space(3)))
; __device__ __forceinline__ float row_rstd(const float* ssq, int row, int fq) {
;     const f32x4 s = *(const f32x4*)(ssq + (size_t)row * 16 + 4 * fq);
;     float t = (s[0] + s[1]) + (s[2] + s[3]);
;     t += __shfl_xor(t, 16); t += __shfl_xor(t, 32);
;     return rsqrtf(t * (1.0f / DM) + EPS);
; }
; __device__ __forceinline__ bool rc_hit(LAS float* rc, const int want, const int wave) { return __builtin_amdgcn_readfirstlane(*(volatile LAS int*)((LAS int*)(rc + 1024) + wave)) == want; }
; __device__ __forceinline__ float rc_get(LAS float* rc, const bool hit, const float* ssq, const int row, const int wave, const int slot, const int fr, const int fq) {
;     LAS float* e = rc + wave * 128 + slot * 16 + fr;
;     if (hit) return *e;
;     const float r = row_rstd(ssq, row, fq); if (fq == 0) *e = r; return r;
.LBB0_753:
	s_nop 1
	v_add_u32_e32 v36, 0xa0, v166
	v_ashrrev_i32_e32 v37, 31, v36
	s_and_b64 vcc, exec, s[12:13]
	s_mov_b64 s[38:39], -1
	s_cbranch_vccnz .LBB0_757
	v_lshlrev_b64 v[34:35], 6, v[36:37]
	v_lshl_add_u64 v[34:35], v[158:159], 0, v[34:35]
	s_waitcnt vmcnt(7)
	v_mov_b32_e32 v38, v232
	v_mov_b32_e32 v39, v233
	v_mov_b32_e32 v40, v234
	v_mov_b32_e32 v41, v235
	v_mov_b32_e32 v34, v39
	v_mov_b32_e32 v35, v40
	v_mov_b32_e32 v39, v41
	v_pk_add_f32 v[34:35], v[34:35], v[38:39]
	s_nop 0
	v_add_f32_e32 v34, v34, v35
	ds_bpermute_b32 v35, v131, v34
	s_waitcnt lgkmcnt(0)
	v_add_f32_e32 v34, v34, v35
	ds_bpermute_b32 v35, v135, v34
	s_waitcnt lgkmcnt(0)
	v_add_f32_e32 v34, v34, v35
	v_fmamk_f32 v34, v34, 0x3a800000, v195
	v_mul_f32_e32 v35, 0x4b800000, v34
	v_cmp_gt_f32_e32 vcc, s68, v34
	s_nop 1
	v_cndmask_b32_e32 v34, v34, v35, vcc
	v_rsq_f32_e32 v34, v34
	s_nop 0
	v_mul_f32_e32 v35, 0x45800000, v34
	v_cndmask_b32_e32 v34, v34, v35, vcc
	s_and_saveexec_b64 s[38:39], s[6:7]
	ds_write_b32 v205, v34 offset:384
	s_or_b64 exec, exec, s[38:39]
	s_mov_b64 s[38:39], 0

; #define LAS __attribute__((address_space(3)))
; __device__ __forceinline__ float row_rstd(const float* ssq, int row, int fq) {
;     const f32x4 s = *(const f32x4*)(ssq + (size_t)row * 16 + 4 * fq);
;     float t = (s[0] + s[1]) + (s[2] + s[3]);
;     t += __shfl_xor(t, 16); t += __shfl_xor(t, 32);
;     return rsqrtf(t * (1.0f / DM) + EPS);
; }
; __device__ __forceinline__ bool rc_hit(LAS float* rc, const int want, const int wave) { return __builtin_amdgcn_readfirstlane(*(volatile LAS int*)((LAS int*)(rc + 1024) + wave)) == want; }
; __device__ __forceinline__ float rc_get(LAS float* rc, const bool hit, const float* ssq, const int row, const int wave, const int slot, const int fr, const int fq) {
;     LAS float* e = rc + wave * 128 + slot * 16 + fr;
;     if (hit) return *e;
;     const float r = row_rstd(ssq, row, fq); if (fq == 0) *e = r; return r;
.LBB0_778:
	s_nop 1
	v_add_u32_e32 v20, 0xb0, v166
	v_ashrrev_i32_e32 v21, 31, v20
	s_and_b64 vcc, exec, s[12:13]
	s_mov_b64 s[12:13], -1
	s_cbranch_vccnz .LBB0_782
	v_lshlrev_b64 v[18:19], 6, v[20:21]
	v_lshl_add_u64 v[18:19], v[158:159], 0, v[18:19]
	s_waitcnt vmcnt(7)
	v_mov_b32_e32 v22, v236
	v_mov_b32_e32 v23, v237
	v_mov_b32_e32 v24, v238
	v_mov_b32_e32 v25, v239
	v_mov_b32_e32 v18, v23
	v_mov_b32_e32 v19, v24
	v_mov_b32_e32 v23, v25
	v_pk_add_f32 v[18:19], v[18:19], v[22:23]
	s_nop 0
	v_add_f32_e32 v18, v18, v19
	ds_bpermute_b32 v19, v131, v18
	s_waitcnt lgkmcnt(0)
	v_add_f32_e32 v18, v18, v19
	ds_bpermute_b32 v19, v135, v18
	s_waitcnt lgkmcnt(0)
	v_add_f32_e32 v18, v18, v19
	v_fmamk_f32 v18, v18, 0x3a800000, v195
	v_mul_f32_e32 v19, 0x4b800000, v18
	v_cmp_gt_f32_e32 vcc, s68, v18
	s_nop 1
	v_cndmask_b32_e32 v18, v18, v19, vcc
	v_rsq_f32_e32 v18, v18
	s_nop 0
	v_mul_f32_e32 v19, 0x45800000, v18
	v_cndmask_b32_e32 v18, v18, v19, vcc
	s_and_saveexec_b64 s[12:13], s[6:7]
	ds_write_b32 v205, v18 offset:448
	s_or_b64 exec, exec, s[12:13]
	s_mov_b64 s[12:13], 0

; #define LAS __attribute__((address_space(3)))
; __device__ __forceinline__ bool rc_hit(LAS float* rc, const int want, const int wave) { return __builtin_amdgcn_readfirstlane(*(volatile LAS int*)((LAS int*)(rc + 1024) + wave)) == want; }
; __device__ __forceinline__ float rc_get(LAS float* rc, const bool hit, const float* ssq, const int row, const int wave, const int slot, const int fr, const int fq) {
;     LAS float* e = rc + wave * 128 + slot * 16 + fr;
;     if (hit) return *e;
;     const float r = row_rstd(ssq, row, fq); if (fq == 0) *e = r; return r;
;     __device__ __forceinline__ void operator()(const f32x4 (&acc)[2][2][4][2], const pg8::Unit& u, int wr, int wc, int fr, int fq) const {
;     ...
;         const int rcw = wr * 4 + wc, rcwant = salt * 1024 + u.pm + 1; const bool rchit = rc_hit(rc, rcwant, rcw);
; #pragma unroll
;         for (int ai = 0; ai < 2; ++ai)
; #pragma unroll
;             for (int m = 0; m < 4; ++m) {
;                 const int row = row0 + ai * 128 + m * 16; const float rs = rc_get(rc, rchit, ssq, row, rcw, ai * 4 + m, fr, fq);
.LBB0_1767:
	v_mov_b32_e32 v164, v1
	v_mov_b32_e32 v165, s46
	ds_read_b32 v165, v165
	s_lshl_b32 s4, s49, 8
	s_add_i32 s4, s4, s41
	v_add_u32_e32 v166, s4, v164
	s_add_i32 s21, s45, s49
	s_waitcnt lgkmcnt(0)
	v_readfirstlane_b32 s4, v165
	s_cmp_lg_u32 s4, s21
	s_cselect_b64 s[28:29], -1, 0
	v_lshl_add_u32 v171, v164, 2, s47
	v_ashrrev_i32_e32 v167, 31, v166
	s_mov_b64 s[12:13], -1
	s_and_b64 vcc, exec, s[28:29]
	s_cbranch_vccz .LBB0_1771
	v_lshlrev_b64 v[164:165], 6, v[166:167]
	v_lshl_add_u64 v[164:165], v[158:159], 0, v[164:165]
	s_mov_b32 s100, 0x2000
	s_mov_b32 s101, 0
	v_lshl_add_u64 v[240:241], v[164:165], 0, s[100:101]
	global_load_dwordx4 v[208:211], v[164:165], off
	global_load_dwordx4 v[212:215], v[164:165], off offset:1024
	global_load_dwordx4 v[216:219], v[164:165], off offset:2048
	global_load_dwordx4 v[220:223], v[164:165], off offset:3072
	global_load_dwordx4 v[224:227], v[240:241], off
	global_load_dwordx4 v[228:231], v[240:241], off offset:1024
	global_load_dwordx4 v[232:235], v[240:241], off offset:2048
	global_load_dwordx4 v[236:239], v[240:241], off offset:3072
	s_waitcnt vmcnt(7)
	v_mov_b32_e32 v172, v208
	v_mov_b32_e32 v173, v209
	v_mov_b32_e32 v174, v210
	v_mov_b32_e32 v175, v211
	v_mov_b32_e32 v164, v173
	v_mov_b32_e32 v165, v174
	v_mov_b32_e32 v173, v175
	v_pk_add_f32 v[164:165], v[164:165], v[172:173]
	s_nop 0
	v_add_f32_e32 v164, v164, v165
	ds_bpermute_b32 v165, v131, v164
	s_waitcnt lgkmcnt(0)
	v_add_f32_e32 v164, v164, v165
	ds_bpermute_b32 v165, v135, v164
	s_waitcnt lgkmcnt(0)
	v_add_f32_e32 v164, v164, v165
	v_fmamk_f32 v164, v164, 0x3a800000, v195
	v_mul_f32_e32 v165, 0x4b800000, v164
	v_cmp_gt_f32_e32 vcc, s68, v164
	s_nop 1
	v_cndmask_b32_e32 v164, v164, v165, vcc
	v_rsq_f32_e32 v164, v164
	s_nop 0
	v_mul_f32_e32 v165, 0x45800000, v164
	v_cndmask_b32_e32 v172, v164, v165, vcc
	s_and_saveexec_b64 s[12:13], s[8:9]
	ds_write_b32 v171, v172
	s_or_b64 exec, exec, s[12:13]
	s_mov_b64 s[12:13], 0

; #define LAS __attribute__((address_space(3)))
; __device__ __forceinline__ unsigned pk_bf16(float lo, float hi) { const f32x2 v = {lo, hi}; const bf16x2_t b = __builtin_convertvector(v, bf16x2_t); return __builtin_bit_cast(unsigned, b); }
; __device__ __forceinline__ float row_rstd(const float* ssq, int row, int fq) {
;     const f32x4 s = *(const f32x4*)(ssq + (size_t)row * 16 + 4 * fq);
;     float t = (s[0] + s[1]) + (s[2] + s[3]);
;     t += __shfl_xor(t, 16); t += __shfl_xor(t, 32);
;     return rsqrtf(t * (1.0f / DM) + EPS);
; }
; __device__ __forceinline__ bool rc_hit(LAS float* rc, const int want, const int wave) { return __builtin_amdgcn_readfirstlane(*(volatile LAS int*)((LAS int*)(rc + 1024) + wave)) == want; }
; __device__ __forceinline__ float rc_get(LAS float* rc, const bool hit, const float* ssq, const int row, const int wave, const int slot, const int fr, const int fq) {
;     LAS float* e = rc + wave * 128 + slot * 16 + fr;
;     if (hit) return *e;
;     const float r = row_rstd(ssq, row, fq); if (fq == 0) *e = r; return r;
;     __device__ __forceinline__ void operator()(const f32x4 (&acc)[2][2][4][2], const pg8::Unit& u, int wr, int wc, int fr, int fq) const {
;     ...
;                 const int row = row0 + ai * 128 + m * 16; const float rs = rc_get(rc, rchit, ssq, row, rcw, ai * 4 + m, fr, fq);
;                 float h[8];
;                 const float c1 = rs * -1.4426950408889634f, rs2 = rs * rs;
; #pragma unroll
;                 for (int n = 0; n < 2; ++n)
; #pragma unroll
;                     for (int j = 0; j < 4; j += 2) { const f32x2 ag = {acc[ai][0][m][n][j], acc[ai][0][m][n][j + 1]}, au = {acc[ai][1][m][n][j], acc[ai][1][m][n][j + 1]};
;                         const f32x2 t = ag * c1; f32x2 e; e.x = __builtin_amdgcn_exp2f(t.x); e.y = __builtin_amdgcn_exp2f(t.y);
;                         const f32x2 d = e + 1.0f; f32x2 r; r.x = __builtin_amdgcn_rcpf(d.x); r.y = __builtin_amdgcn_rcpf(d.y);
;                         const f32x2 hh = (ag * au) * (r * rs2); h[n * 4 + j] = hh.x; h[n * 4 + j + 1] = hh.y; }
;                 u32x4 w; w.x = pk_bf16(h[0], h[1]); w.y = pk_bf16(h[2], h[3]); w.z = pk_bf16(h[4], h[5]); w.w = pk_bf16(h[6], h[7]);
;                 __builtin_nontemporal_store(w, (u32x4*)(H + (size_t)row * DFF + col0));
.LBB0_1773:
	s_waitcnt lgkmcnt(0)
	v_mul_f32_e32 v174, 0xbfb8aa3b, v172
	v_pk_mul_f32 v[176:177], v[126:127], v[174:175] op_sel_hi:[1,0]
	v_mul_f32_e32 v172, v172, v172
	v_exp_f32_e32 v176, v176
	v_exp_f32_e32 v177, v177
	v_pk_mul_f32 v[122:123], v[126:127], v[122:123]
	v_pk_mul_f32 v[124:125], v[128:129], v[124:125]
	v_lshl_or_b32 v164, s48, 7, v169
	v_pk_add_f32 v[176:177], v[176:177], 1.0 op_sel_hi:[1,0]
	v_pk_mul_f32 v[120:121], v[116:117], v[120:121]
	v_rcp_f32_e32 v176, v176
	v_rcp_f32_e32 v177, v177
	v_ashrrev_i32_e32 v165, 31, v164
	s_mov_b64 s[30:31], -1
	s_andn2_b64 vcc, exec, s[28:29]
	v_pk_mul_f32 v[126:127], v[172:173], v[176:177] op_sel_hi:[0,1]
	v_pk_mul_f32 v[122:123], v[122:123], v[126:127]
	v_pk_mul_f32 v[126:127], v[128:129], v[174:175] op_sel_hi:[1,0]
	s_nop 0
	v_exp_f32_e32 v126, v126
	v_exp_f32_e32 v127, v127
	s_nop 0
	v_pk_add_f32 v[126:127], v[126:127], 1.0 op_sel_hi:[1,0]
	s_nop 0
	v_rcp_f32_e32 v126, v126
	v_rcp_f32_e32 v127, v127
	s_nop 0
	v_pk_mul_f32 v[126:127], v[172:173], v[126:127] op_sel_hi:[0,1]
	v_pk_mul_f32 v[124:125], v[124:125], v[126:127]
	v_pk_mul_f32 v[126:127], v[114:115], v[174:175] op_sel_hi:[1,0]
	v_pk_mul_f32 v[114:115], v[114:115], v[118:119]
	v_exp_f32_e32 v126, v126
	v_exp_f32_e32 v127, v127
	s_nop 0
	v_pk_add_f32 v[126:127], v[126:127], 1.0 op_sel_hi:[1,0]
	s_nop 0
	v_rcp_f32_e32 v126, v126
	v_rcp_f32_e32 v127, v127
	s_nop 0
	v_pk_mul_f32 v[118:119], v[172:173], v[126:127] op_sel_hi:[0,1]
	v_pk_mul_f32 v[118:119], v[114:115], v[118:119]
	v_pk_mul_f32 v[114:115], v[116:117], v[174:175] op_sel_hi:[1,0]
	v_cvt_pk_bf16_f32 v116, v118, v119
	v_exp_f32_e32 v114, v114
	v_exp_f32_e32 v115, v115
	v_mov_b64_e32 v[118:119], s[16:17]
	v_mad_i64_i32 v[118:119], s[4:5], v166, s87, v[118:119]
	v_pk_add_f32 v[114:115], v[114:115], 1.0 op_sel_hi:[1,0]
	v_lshl_add_u64 v[118:119], v[164:165], 1, v[118:119]
	v_rcp_f32_e32 v114, v114
	v_rcp_f32_e32 v115, v115
	s_nop 0
	v_pk_mul_f32 v[114:115], v[172:173], v[114:115] op_sel_hi:[0,1]
	v_pk_mul_f32 v[120:121], v[120:121], v[114:115]
	v_cvt_pk_bf16_f32 v114, v122, v123
	v_cvt_pk_bf16_f32 v115, v124, v125
	v_cvt_pk_bf16_f32 v117, v120, v121
	global_store_dwordx4 v[118:119], v[114:117], off nt
	s_nop 1
	v_add_u32_e32 v114, 16, v166
	v_cndmask_b32_e64 v116, 0, 1, s[28:29]
	v_ashrrev_i32_e32 v115, 31, v114
	v_cmp_ne_u32_e64 s[12:13], 1, v116
	s_cbranch_vccnz .LBB0_1777
	v_lshlrev_b64 v[116:117], 6, v[114:115]
	v_lshl_add_u64 v[116:117], v[158:159], 0, v[116:117]
	s_waitcnt vmcnt(7)
	v_mov_b32_e32 v116, v212
	v_mov_b32_e32 v117, v213
	v_mov_b32_e32 v118, v214
	v_mov_b32_e32 v119, v215
	v_mov_b32_e32 v120, v117
	v_mov_b32_e32 v121, v118
	v_mov_b32_e32 v117, v119
	v_pk_add_f32 v[116:117], v[120:121], v[116:117]
	s_nop 0
	v_add_f32_e32 v115, v116, v117
	ds_bpermute_b32 v116, v131, v115
	s_waitcnt lgkmcnt(0)
	v_add_f32_e32 v115, v115, v116
	ds_bpermute_b32 v116, v135, v115
	s_waitcnt lgkmcnt(0)
	v_add_f32_e32 v115, v115, v116
	v_fmamk_f32 v115, v115, 0x3a800000, v195
	v_mul_f32_e32 v116, 0x4b800000, v115
	v_cmp_gt_f32_e32 vcc, s68, v115
	s_nop 1
	v_cndmask_b32_e32 v115, v115, v116, vcc
	v_rsq_f32_e32 v115, v115
	s_nop 0
	v_mul_f32_e32 v116, 0x45800000, v115
	v_cndmask_b32_e32 v116, v115, v116, vcc
	s_and_saveexec_b64 s[30:31], s[8:9]
	ds_write_b32 v171, v116 offset:64
	s_or_b64 exec, exec, s[30:31]
	s_mov_b64 s[30:31], 0

; #define LAS __attribute__((address_space(3)))
; __device__ __forceinline__ unsigned pk_bf16(float lo, float hi) { const f32x2 v = {lo, hi}; const bf16x2_t b = __builtin_convertvector(v, bf16x2_t); return __builtin_bit_cast(unsigned, b); }
; __device__ __forceinline__ float row_rstd(const float* ssq, int row, int fq) {
;     const f32x4 s = *(const f32x4*)(ssq + (size_t)row * 16 + 4 * fq);
;     float t = (s[0] + s[1]) + (s[2] + s[3]);
;     t += __shfl_xor(t, 16); t += __shfl_xor(t, 32);
;     return rsqrtf(t * (1.0f / DM) + EPS);
; }
; __device__ __forceinline__ bool rc_hit(LAS float* rc, const int want, const int wave) { return __builtin_amdgcn_readfirstlane(*(volatile LAS int*)((LAS int*)(rc + 1024) + wave)) == want; }
; __device__ __forceinline__ float rc_get(LAS float* rc, const bool hit, const float* ssq, const int row, const int wave, const int slot, const int fr, const int fq) {
;     LAS float* e = rc + wave * 128 + slot * 16 + fr;
;     if (hit) return *e;
;     const float r = row_rstd(ssq, row, fq); if (fq == 0) *e = r; return r;
;     __device__ __forceinline__ void operator()(const f32x4 (&acc)[2][2][4][2], const pg8::Unit& u, int wr, int wc, int fr, int fq) const {
;     ...
;                 const int row = row0 + ai * 128 + m * 16; const float rs = rc_get(rc, rchit, ssq, row, rcw, ai * 4 + m, fr, fq);
;                 float h[8];
;                 const float c1 = rs * -1.4426950408889634f, rs2 = rs * rs;
; #pragma unroll
;                 for (int n = 0; n < 2; ++n)
; #pragma unroll
;                     for (int j = 0; j < 4; j += 2) { const f32x2 ag = {acc[ai][0][m][n][j], acc[ai][0][m][n][j + 1]}, au = {acc[ai][1][m][n][j], acc[ai][1][m][n][j + 1]};
;                         const f32x2 t = ag * c1; f32x2 e; e.x = __builtin_amdgcn_exp2f(t.x); e.y = __builtin_amdgcn_exp2f(t.y);
;                         const f32x2 d = e + 1.0f; f32x2 r; r.x = __builtin_amdgcn_rcpf(d.x); r.y = __builtin_amdgcn_rcpf(d.y);
;                         const f32x2 hh = (ag * au) * (r * rs2); h[n * 4 + j] = hh.x; h[n * 4 + j + 1] = hh.y; }
;                 u32x4 w; w.x = pk_bf16(h[0], h[1]); w.y = pk_bf16(h[2], h[3]); w.z = pk_bf16(h[4], h[5]); w.w = pk_bf16(h[6], h[7]);
;                 __builtin_nontemporal_store(w, (u32x4*)(H + (size_t)row * DFF + col0));
.LBB0_1779:
	s_waitcnt lgkmcnt(0)
	v_mul_f32_e32 v118, 0xbfb8aa3b, v116
	v_pk_mul_f32 v[120:121], v[110:111], v[118:119] op_sel_hi:[1,0]
	v_mul_f32_e32 v116, v116, v116
	v_exp_f32_e32 v120, v120
	v_exp_f32_e32 v121, v121
	v_pk_mul_f32 v[106:107], v[110:111], v[106:107]
	v_pk_mul_f32 v[108:109], v[112:113], v[108:109]
	v_pk_mul_f32 v[104:105], v[100:101], v[104:105]
	v_pk_add_f32 v[120:121], v[120:121], 1.0 op_sel_hi:[1,0]
	s_mov_b64 s[30:31], -1
	v_rcp_f32_e32 v120, v120
	v_rcp_f32_e32 v121, v121
	s_and_b64 vcc, exec, s[12:13]
	v_pk_mul_f32 v[110:111], v[116:117], v[120:121] op_sel_hi:[0,1]
	v_pk_mul_f32 v[106:107], v[106:107], v[110:111]
	v_pk_mul_f32 v[110:111], v[112:113], v[118:119] op_sel_hi:[1,0]
	s_nop 0
	v_exp_f32_e32 v110, v110
	v_exp_f32_e32 v111, v111
	s_nop 0
	v_pk_add_f32 v[110:111], v[110:111], 1.0 op_sel_hi:[1,0]
	s_nop 0
	v_rcp_f32_e32 v110, v110
	v_rcp_f32_e32 v111, v111
	s_nop 0
	v_pk_mul_f32 v[110:111], v[116:117], v[110:111] op_sel_hi:[0,1]
	v_pk_mul_f32 v[108:109], v[108:109], v[110:111]
	v_pk_mul_f32 v[110:111], v[98:99], v[118:119] op_sel_hi:[1,0]
	v_pk_mul_f32 v[98:99], v[98:99], v[102:103]
	v_exp_f32_e32 v110, v110
	v_exp_f32_e32 v111, v111
	s_nop 0
	v_pk_add_f32 v[110:111], v[110:111], 1.0 op_sel_hi:[1,0]
	s_nop 0
	v_rcp_f32_e32 v110, v110
	v_rcp_f32_e32 v111, v111
	s_nop 0
	v_pk_mul_f32 v[102:103], v[116:117], v[110:111] op_sel_hi:[0,1]
	v_pk_mul_f32 v[102:103], v[98:99], v[102:103]
	v_pk_mul_f32 v[98:99], v[100:101], v[118:119] op_sel_hi:[1,0]
	v_cvt_pk_bf16_f32 v100, v102, v103
	v_exp_f32_e32 v98, v98
	v_exp_f32_e32 v99, v99
	v_mov_b64_e32 v[102:103], s[16:17]
	v_mad_i64_i32 v[102:103], s[4:5], v114, s87, v[102:103]
	v_pk_add_f32 v[98:99], v[98:99], 1.0 op_sel_hi:[1,0]
	v_lshl_add_u64 v[102:103], v[164:165], 1, v[102:103]
	v_rcp_f32_e32 v98, v98
	v_rcp_f32_e32 v99, v99
	s_nop 0
	v_pk_mul_f32 v[98:99], v[116:117], v[98:99] op_sel_hi:[0,1]
	v_pk_mul_f32 v[104:105], v[104:105], v[98:99]
	v_cvt_pk_bf16_f32 v98, v106, v107
	v_cvt_pk_bf16_f32 v99, v108, v109
	v_cvt_pk_bf16_f32 v101, v104, v105
	global_store_dwordx4 v[102:103], v[98:101], off nt
	s_nop 1
	v_add_u32_e32 v98, 32, v166
	v_ashrrev_i32_e32 v99, 31, v98
	s_cbranch_vccnz .LBB0_1783
	v_lshlrev_b64 v[100:101], 6, v[98:99]
	v_lshl_add_u64 v[100:101], v[158:159], 0, v[100:101]
	s_waitcnt vmcnt(7)
	v_mov_b32_e32 v100, v216
	v_mov_b32_e32 v101, v217
	v_mov_b32_e32 v102, v218
	v_mov_b32_e32 v103, v219
	v_mov_b32_e32 v104, v101
	v_mov_b32_e32 v105, v102
	v_mov_b32_e32 v101, v103
	v_pk_add_f32 v[100:101], v[104:105], v[100:101]
	s_nop 0
	v_add_f32_e32 v99, v100, v101
	ds_bpermute_b32 v100, v131, v99
	s_waitcnt lgkmcnt(0)
	v_add_f32_e32 v99, v99, v100
	ds_bpermute_b32 v100, v135, v99
	s_waitcnt lgkmcnt(0)
	v_add_f32_e32 v99, v99, v100
	v_fmamk_f32 v99, v99, 0x3a800000, v195
	v_mul_f32_e32 v100, 0x4b800000, v99
	v_cmp_gt_f32_e32 vcc, s68, v99
	s_nop 1
	v_cndmask_b32_e32 v99, v99, v100, vcc
	v_rsq_f32_e32 v99, v99
	s_nop 0
	v_mul_f32_e32 v100, 0x45800000, v99
	v_cndmask_b32_e32 v100, v99, v100, vcc
	s_and_saveexec_b64 s[30:31], s[8:9]
	ds_write_b32 v171, v100 offset:128
	s_or_b64 exec, exec, s[30:31]
	s_mov_b64 s[30:31], 0

; #define LAS __attribute__((address_space(3)))
; __device__ __forceinline__ unsigned pk_bf16(float lo, float hi) { const f32x2 v = {lo, hi}; const bf16x2_t b = __builtin_convertvector(v, bf16x2_t); return __builtin_bit_cast(unsigned, b); }
; __device__ __forceinline__ float row_rstd(const float* ssq, int row, int fq) {
;     const f32x4 s = *(const f32x4*)(ssq + (size_t)row * 16 + 4 * fq);
;     float t = (s[0] + s[1]) + (s[2] + s[3]);
;     t += __shfl_xor(t, 16); t += __shfl_xor(t, 32);
;     return rsqrtf(t * (1.0f / DM) + EPS);
; }
; __device__ __forceinline__ bool rc_hit(LAS float* rc, const int want, const int wave) { return __builtin_amdgcn_readfirstlane(*(volatile LAS int*)((LAS int*)(rc + 1024) + wave)) == want; }
; __device__ __forceinline__ float rc_get(LAS float* rc, const bool hit, const float* ssq, const int row, const int wave, const int slot, const int fr, const int fq) {
;     LAS float* e = rc + wave * 128 + slot * 16 + fr;
;     if (hit) return *e;
;     const float r = row_rstd(ssq, row, fq); if (fq == 0) *e = r; return r;
;     __device__ __forceinline__ void operator()(const f32x4 (&acc)[2][2][4][2], const pg8::Unit& u, int wr, int wc, int fr, int fq) const {
;     ...
;                 const int row = row0 + ai * 128 + m * 16; const float rs = rc_get(rc, rchit, ssq, row, rcw, ai * 4 + m, fr, fq);
;                 float h[8];
;                 const float c1 = rs * -1.4426950408889634f, rs2 = rs * rs;
; #pragma unroll
;                 for (int n = 0; n < 2; ++n)
; #pragma unroll
;                     for (int j = 0; j < 4; j += 2) { const f32x2 ag = {acc[ai][0][m][n][j], acc[ai][0][m][n][j + 1]}, au = {acc[ai][1][m][n][j], acc[ai][1][m][n][j + 1]};
;                         const f32x2 t = ag * c1; f32x2 e; e.x = __builtin_amdgcn_exp2f(t.x); e.y = __builtin_amdgcn_exp2f(t.y);
;                         const f32x2 d = e + 1.0f; f32x2 r; r.x = __builtin_amdgcn_rcpf(d.x); r.y = __builtin_amdgcn_rcpf(d.y);
;                         const f32x2 hh = (ag * au) * (r * rs2); h[n * 4 + j] = hh.x; h[n * 4 + j + 1] = hh.y; }
;                 u32x4 w; w.x = pk_bf16(h[0], h[1]); w.y = pk_bf16(h[2], h[3]); w.z = pk_bf16(h[4], h[5]); w.w = pk_bf16(h[6], h[7]);
;                 __builtin_nontemporal_store(w, (u32x4*)(H + (size_t)row * DFF + col0));
.LBB0_1785:
	s_waitcnt lgkmcnt(0)
	v_mul_f32_e32 v102, 0xbfb8aa3b, v100
	v_pk_mul_f32 v[104:105], v[94:95], v[102:103] op_sel_hi:[1,0]
	v_mul_f32_e32 v100, v100, v100
	v_exp_f32_e32 v104, v104
	v_exp_f32_e32 v105, v105
	v_pk_mul_f32 v[90:91], v[94:95], v[90:91]
	v_pk_mul_f32 v[92:93], v[96:97], v[92:93]
	v_pk_mul_f32 v[88:89], v[84:85], v[88:89]
	v_pk_add_f32 v[104:105], v[104:105], 1.0 op_sel_hi:[1,0]
	s_mov_b64 s[30:31], -1
	v_rcp_f32_e32 v104, v104
	v_rcp_f32_e32 v105, v105
	s_and_b64 vcc, exec, s[12:13]
	v_pk_mul_f32 v[94:95], v[100:101], v[104:105] op_sel_hi:[0,1]
	v_pk_mul_f32 v[90:91], v[90:91], v[94:95]
	v_pk_mul_f32 v[94:95], v[96:97], v[102:103] op_sel_hi:[1,0]
	s_nop 0
	v_exp_f32_e32 v94, v94
	v_exp_f32_e32 v95, v95
	s_nop 0
	v_pk_add_f32 v[94:95], v[94:95], 1.0 op_sel_hi:[1,0]
	s_nop 0
	v_rcp_f32_e32 v94, v94
	v_rcp_f32_e32 v95, v95
	s_nop 0
	v_pk_mul_f32 v[94:95], v[100:101], v[94:95] op_sel_hi:[0,1]
	v_pk_mul_f32 v[92:93], v[92:93], v[94:95]
	v_pk_mul_f32 v[94:95], v[82:83], v[102:103] op_sel_hi:[1,0]
	v_pk_mul_f32 v[82:83], v[82:83], v[86:87]
	v_exp_f32_e32 v94, v94
	v_exp_f32_e32 v95, v95
	s_nop 0
	v_pk_add_f32 v[94:95], v[94:95], 1.0 op_sel_hi:[1,0]
	s_nop 0
	v_rcp_f32_e32 v94, v94
	v_rcp_f32_e32 v95, v95
	s_nop 0
	v_pk_mul_f32 v[86:87], v[100:101], v[94:95] op_sel_hi:[0,1]
	v_pk_mul_f32 v[86:87], v[82:83], v[86:87]
	v_pk_mul_f32 v[82:83], v[84:85], v[102:103] op_sel_hi:[1,0]
	v_cvt_pk_bf16_f32 v84, v86, v87
	v_exp_f32_e32 v82, v82
	v_exp_f32_e32 v83, v83
	v_mov_b64_e32 v[86:87], s[16:17]
	v_mad_i64_i32 v[86:87], s[4:5], v98, s87, v[86:87]
	v_pk_add_f32 v[82:83], v[82:83], 1.0 op_sel_hi:[1,0]
	v_lshl_add_u64 v[86:87], v[164:165], 1, v[86:87]
	v_rcp_f32_e32 v82, v82
	v_rcp_f32_e32 v83, v83
	s_nop 0
	v_pk_mul_f32 v[82:83], v[100:101], v[82:83] op_sel_hi:[0,1]
	v_pk_mul_f32 v[88:89], v[88:89], v[82:83]
	v_cvt_pk_bf16_f32 v82, v90, v91
	v_cvt_pk_bf16_f32 v83, v92, v93
	v_cvt_pk_bf16_f32 v85, v88, v89
	global_store_dwordx4 v[86:87], v[82:85], off nt
	s_nop 1
	v_add_u32_e32 v82, 48, v166
	v_ashrrev_i32_e32 v83, 31, v82
	s_cbranch_vccnz .LBB0_1789
	v_lshlrev_b64 v[84:85], 6, v[82:83]
	v_lshl_add_u64 v[84:85], v[158:159], 0, v[84:85]
	s_waitcnt vmcnt(7)
	v_mov_b32_e32 v84, v220
	v_mov_b32_e32 v85, v221
	v_mov_b32_e32 v86, v222
	v_mov_b32_e32 v87, v223
	v_mov_b32_e32 v88, v85
	v_mov_b32_e32 v89, v86
	v_mov_b32_e32 v85, v87
	v_pk_add_f32 v[84:85], v[88:89], v[84:85]
	s_nop 0
	v_add_f32_e32 v83, v84, v85
	ds_bpermute_b32 v84, v131, v83
	s_waitcnt lgkmcnt(0)
	v_add_f32_e32 v83, v83, v84
	ds_bpermute_b32 v84, v135, v83
	s_waitcnt lgkmcnt(0)
	v_add_f32_e32 v83, v83, v84
	v_fmamk_f32 v83, v83, 0x3a800000, v195
	v_mul_f32_e32 v84, 0x4b800000, v83
	v_cmp_gt_f32_e32 vcc, s68, v83
	s_nop 1
	v_cndmask_b32_e32 v83, v83, v84, vcc
	v_rsq_f32_e32 v83, v83
	s_nop 0
	v_mul_f32_e32 v84, 0x45800000, v83
	v_cndmask_b32_e32 v84, v83, v84, vcc
	s_and_saveexec_b64 s[30:31], s[8:9]
	ds_write_b32 v171, v84 offset:192
	s_or_b64 exec, exec, s[30:31]
	s_mov_b64 s[30:31], 0

; #define LAS __attribute__((address_space(3)))
; __device__ __forceinline__ unsigned pk_bf16(float lo, float hi) { const f32x2 v = {lo, hi}; const bf16x2_t b = __builtin_convertvector(v, bf16x2_t); return __builtin_bit_cast(unsigned, b); }
; __device__ __forceinline__ float row_rstd(const float* ssq, int row, int fq) {
;     const f32x4 s = *(const f32x4*)(ssq + (size_t)row * 16 + 4 * fq);
;     float t = (s[0] + s[1]) + (s[2] + s[3]);
;     t += __shfl_xor(t, 16); t += __shfl_xor(t, 32);
;     return rsqrtf(t * (1.0f / DM) + EPS);
; }
; __device__ __forceinline__ bool rc_hit(LAS float* rc, const int want, const int wave) { return __builtin_amdgcn_readfirstlane(*(volatile LAS int*)((LAS int*)(rc + 1024) + wave)) == want; }
; __device__ __forceinline__ float rc_get(LAS float* rc, const bool hit, const float* ssq, const int row, const int wave, const int slot, const int fr, const int fq) {
;     LAS float* e = rc + wave * 128 + slot * 16 + fr;
;     if (hit) return *e;
;     const float r = row_rstd(ssq, row, fq); if (fq == 0) *e = r; return r;
;     __device__ __forceinline__ void operator()(const f32x4 (&acc)[2][2][4][2], const pg8::Unit& u, int wr, int wc, int fr, int fq) const {
;     ...
;                 const int row = row0 + ai * 128 + m * 16; const float rs = rc_get(rc, rchit, ssq, row, rcw, ai * 4 + m, fr, fq);
;                 float h[8];
;                 const float c1 = rs * -1.4426950408889634f, rs2 = rs * rs;
; #pragma unroll
;                 for (int n = 0; n < 2; ++n)
; #pragma unroll
;                     for (int j = 0; j < 4; j += 2) { const f32x2 ag = {acc[ai][0][m][n][j], acc[ai][0][m][n][j + 1]}, au = {acc[ai][1][m][n][j], acc[ai][1][m][n][j + 1]};
;                         const f32x2 t = ag * c1; f32x2 e; e.x = __builtin_amdgcn_exp2f(t.x); e.y = __builtin_amdgcn_exp2f(t.y);
;                         const f32x2 d = e + 1.0f; f32x2 r; r.x = __builtin_amdgcn_rcpf(d.x); r.y = __builtin_amdgcn_rcpf(d.y);
;                         const f32x2 hh = (ag * au) * (r * rs2); h[n * 4 + j] = hh.x; h[n * 4 + j + 1] = hh.y; }
;                 u32x4 w; w.x = pk_bf16(h[0], h[1]); w.y = pk_bf16(h[2], h[3]); w.z = pk_bf16(h[4], h[5]); w.w = pk_bf16(h[6], h[7]);
;                 __builtin_nontemporal_store(w, (u32x4*)(H + (size_t)row * DFF + col0));
.LBB0_1791:
	s_waitcnt lgkmcnt(0)
	v_mul_f32_e32 v86, 0xbfb8aa3b, v84
	v_pk_mul_f32 v[88:89], v[78:79], v[86:87] op_sel_hi:[1,0]
	v_mul_f32_e32 v84, v84, v84
	v_exp_f32_e32 v88, v88
	v_exp_f32_e32 v89, v89
	v_pk_mul_f32 v[74:75], v[78:79], v[74:75]
	v_pk_mul_f32 v[76:77], v[80:81], v[76:77]
	v_pk_mul_f32 v[72:73], v[68:69], v[72:73]
	v_pk_add_f32 v[88:89], v[88:89], 1.0 op_sel_hi:[1,0]
	s_mov_b64 s[30:31], -1
	v_rcp_f32_e32 v88, v88
	v_rcp_f32_e32 v89, v89
	s_and_b64 vcc, exec, s[12:13]
	v_pk_mul_f32 v[78:79], v[84:85], v[88:89] op_sel_hi:[0,1]
	v_pk_mul_f32 v[74:75], v[74:75], v[78:79]
	v_pk_mul_f32 v[78:79], v[80:81], v[86:87] op_sel_hi:[1,0]
	s_nop 0
	v_exp_f32_e32 v78, v78
	v_exp_f32_e32 v79, v79
	s_nop 0
	v_pk_add_f32 v[78:79], v[78:79], 1.0 op_sel_hi:[1,0]
	s_nop 0
	v_rcp_f32_e32 v78, v78
	v_rcp_f32_e32 v79, v79
	s_nop 0
	v_pk_mul_f32 v[78:79], v[84:85], v[78:79] op_sel_hi:[0,1]
	v_pk_mul_f32 v[76:77], v[76:77], v[78:79]
	v_pk_mul_f32 v[78:79], v[66:67], v[86:87] op_sel_hi:[1,0]
	v_pk_mul_f32 v[66:67], v[66:67], v[70:71]
	v_exp_f32_e32 v78, v78
	v_exp_f32_e32 v79, v79
	s_nop 0
	v_pk_add_f32 v[78:79], v[78:79], 1.0 op_sel_hi:[1,0]
	s_nop 0
	v_rcp_f32_e32 v78, v78
	v_rcp_f32_e32 v79, v79
	s_nop 0
	v_pk_mul_f32 v[70:71], v[84:85], v[78:79] op_sel_hi:[0,1]
	v_pk_mul_f32 v[70:71], v[66:67], v[70:71]
	v_pk_mul_f32 v[66:67], v[68:69], v[86:87] op_sel_hi:[1,0]
	v_cvt_pk_bf16_f32 v68, v70, v71
	v_exp_f32_e32 v66, v66
	v_exp_f32_e32 v67, v67
	v_mov_b64_e32 v[70:71], s[16:17]
	v_mad_i64_i32 v[70:71], s[4:5], v82, s87, v[70:71]
	v_pk_add_f32 v[66:67], v[66:67], 1.0 op_sel_hi:[1,0]
	v_lshl_add_u64 v[70:71], v[164:165], 1, v[70:71]
	v_rcp_f32_e32 v66, v66
	v_rcp_f32_e32 v67, v67
	s_nop 0
	v_pk_mul_f32 v[66:67], v[84:85], v[66:67] op_sel_hi:[0,1]
	v_pk_mul_f32 v[72:73], v[72:73], v[66:67]
	v_cvt_pk_bf16_f32 v66, v74, v75
	v_cvt_pk_bf16_f32 v67, v76, v77
	v_cvt_pk_bf16_f32 v69, v72, v73
	global_store_dwordx4 v[70:71], v[66:69], off nt
	s_nop 1
	v_add_u32_e32 v66, 0x80, v166
	v_ashrrev_i32_e32 v67, 31, v66
	s_cbranch_vccnz .LBB0_1795
	v_lshlrev_b64 v[68:69], 6, v[66:67]
	v_lshl_add_u64 v[68:69], v[158:159], 0, v[68:69]
	s_waitcnt vmcnt(7)
	v_mov_b32_e32 v68, v224
	v_mov_b32_e32 v69, v225
	v_mov_b32_e32 v70, v226
	v_mov_b32_e32 v71, v227
	v_mov_b32_e32 v72, v69
	v_mov_b32_e32 v73, v70
	v_mov_b32_e32 v69, v71
	v_pk_add_f32 v[68:69], v[72:73], v[68:69]
	s_nop 0
	v_add_f32_e32 v67, v68, v69
	ds_bpermute_b32 v68, v131, v67
	s_waitcnt lgkmcnt(0)
	v_add_f32_e32 v67, v67, v68
	ds_bpermute_b32 v68, v135, v67
	s_waitcnt lgkmcnt(0)
	v_add_f32_e32 v67, v67, v68
	v_fmamk_f32 v67, v67, 0x3a800000, v195
	v_mul_f32_e32 v68, 0x4b800000, v67
	v_cmp_gt_f32_e32 vcc, s68, v67
	s_nop 1
	v_cndmask_b32_e32 v67, v67, v68, vcc
	v_rsq_f32_e32 v67, v67
	s_nop 0
	v_mul_f32_e32 v68, 0x45800000, v67
	v_cndmask_b32_e32 v68, v67, v68, vcc
	s_and_saveexec_b64 s[30:31], s[8:9]
	ds_write_b32 v171, v68 offset:256
	s_or_b64 exec, exec, s[30:31]
	s_mov_b64 s[30:31], 0

; #define LAS __attribute__((address_space(3)))
; __device__ __forceinline__ unsigned pk_bf16(float lo, float hi) { const f32x2 v = {lo, hi}; const bf16x2_t b = __builtin_convertvector(v, bf16x2_t); return __builtin_bit_cast(unsigned, b); }
; __device__ __forceinline__ float row_rstd(const float* ssq, int row, int fq) {
;     const f32x4 s = *(const f32x4*)(ssq + (size_t)row * 16 + 4 * fq);
;     float t = (s[0] + s[1]) + (s[2] + s[3]);
;     t += __shfl_xor(t, 16); t += __shfl_xor(t, 32);
;     return rsqrtf(t * (1.0f / DM) + EPS);
; }
; __device__ __forceinline__ bool rc_hit(LAS float* rc, const int want, const int wave) { return __builtin_amdgcn_readfirstlane(*(volatile LAS int*)((LAS int*)(rc + 1024) + wave)) == want; }
; __device__ __forceinline__ float rc_get(LAS float* rc, const bool hit, const float* ssq, const int row, const int wave, const int slot, const int fr, const int fq) {
;     LAS float* e = rc + wave * 128 + slot * 16 + fr;
;     if (hit) return *e;
;     const float r = row_rstd(ssq, row, fq); if (fq == 0) *e = r; return r;
;     __device__ __forceinline__ void operator()(const f32x4 (&acc)[2][2][4][2], const pg8::Unit& u, int wr, int wc, int fr, int fq) const {
;     ...
;                 const int row = row0 + ai * 128 + m * 16; const float rs = rc_get(rc, rchit, ssq, row, rcw, ai * 4 + m, fr, fq);
;                 float h[8];
;                 const float c1 = rs * -1.4426950408889634f, rs2 = rs * rs;
; #pragma unroll
;                 for (int n = 0; n < 2; ++n)
; #pragma unroll
;                     for (int j = 0; j < 4; j += 2) { const f32x2 ag = {acc[ai][0][m][n][j], acc[ai][0][m][n][j + 1]}, au = {acc[ai][1][m][n][j], acc[ai][1][m][n][j + 1]};
;                         const f32x2 t = ag * c1; f32x2 e; e.x = __builtin_amdgcn_exp2f(t.x); e.y = __builtin_amdgcn_exp2f(t.y);
;                         const f32x2 d = e + 1.0f; f32x2 r; r.x = __builtin_amdgcn_rcpf(d.x); r.y = __builtin_amdgcn_rcpf(d.y);
;                         const f32x2 hh = (ag * au) * (r * rs2); h[n * 4 + j] = hh.x; h[n * 4 + j + 1] = hh.y; }
;                 u32x4 w; w.x = pk_bf16(h[0], h[1]); w.y = pk_bf16(h[2], h[3]); w.z = pk_bf16(h[4], h[5]); w.w = pk_bf16(h[6], h[7]);
;                 __builtin_nontemporal_store(w, (u32x4*)(H + (size_t)row * DFF + col0));
.LBB0_1797:
	s_waitcnt lgkmcnt(0)
	v_mul_f32_e32 v70, 0xbfb8aa3b, v68
	v_pk_mul_f32 v[72:73], v[62:63], v[70:71] op_sel_hi:[1,0]
	v_mul_f32_e32 v68, v68, v68
	v_exp_f32_e32 v72, v72
	v_exp_f32_e32 v73, v73
	v_pk_mul_f32 v[58:59], v[62:63], v[58:59]
	v_pk_mul_f32 v[60:61], v[64:65], v[60:61]
	v_pk_mul_f32 v[56:57], v[52:53], v[56:57]
	v_pk_add_f32 v[72:73], v[72:73], 1.0 op_sel_hi:[1,0]
	s_mov_b64 s[30:31], -1
	v_rcp_f32_e32 v72, v72
	v_rcp_f32_e32 v73, v73
	s_and_b64 vcc, exec, s[12:13]
	v_pk_mul_f32 v[62:63], v[68:69], v[72:73] op_sel_hi:[0,1]
	v_pk_mul_f32 v[58:59], v[58:59], v[62:63]
	v_pk_mul_f32 v[62:63], v[64:65], v[70:71] op_sel_hi:[1,0]
	s_nop 0
	v_exp_f32_e32 v62, v62
	v_exp_f32_e32 v63, v63
	s_nop 0
	v_pk_add_f32 v[62:63], v[62:63], 1.0 op_sel_hi:[1,0]
	s_nop 0
	v_rcp_f32_e32 v62, v62
	v_rcp_f32_e32 v63, v63
	s_nop 0
	v_pk_mul_f32 v[62:63], v[68:69], v[62:63] op_sel_hi:[0,1]
	v_pk_mul_f32 v[60:61], v[60:61], v[62:63]
	v_pk_mul_f32 v[62:63], v[50:51], v[70:71] op_sel_hi:[1,0]
	v_pk_mul_f32 v[50:51], v[50:51], v[54:55]
	v_exp_f32_e32 v62, v62
	v_exp_f32_e32 v63, v63
	s_nop 0
	v_pk_add_f32 v[62:63], v[62:63], 1.0 op_sel_hi:[1,0]
	s_nop 0
	v_rcp_f32_e32 v62, v62
	v_rcp_f32_e32 v63, v63
	s_nop 0
	v_pk_mul_f32 v[54:55], v[68:69], v[62:63] op_sel_hi:[0,1]
	v_pk_mul_f32 v[54:55], v[50:51], v[54:55]
	v_pk_mul_f32 v[50:51], v[52:53], v[70:71] op_sel_hi:[1,0]
	v_cvt_pk_bf16_f32 v52, v54, v55
	v_exp_f32_e32 v50, v50
	v_exp_f32_e32 v51, v51
	v_mov_b64_e32 v[54:55], s[16:17]
	v_mad_i64_i32 v[54:55], s[4:5], v66, s87, v[54:55]
	v_pk_add_f32 v[50:51], v[50:51], 1.0 op_sel_hi:[1,0]
	v_lshl_add_u64 v[54:55], v[164:165], 1, v[54:55]
	v_rcp_f32_e32 v50, v50
	v_rcp_f32_e32 v51, v51
	s_nop 0
	v_pk_mul_f32 v[50:51], v[68:69], v[50:51] op_sel_hi:[0,1]
	v_pk_mul_f32 v[56:57], v[56:57], v[50:51]
	v_cvt_pk_bf16_f32 v50, v58, v59
	v_cvt_pk_bf16_f32 v51, v60, v61
	v_cvt_pk_bf16_f32 v53, v56, v57
	global_store_dwordx4 v[54:55], v[50:53], off nt
	s_nop 1
	v_add_u32_e32 v50, 0x90, v166
	v_ashrrev_i32_e32 v51, 31, v50
	s_cbranch_vccnz .LBB0_1801
	v_lshlrev_b64 v[52:53], 6, v[50:51]
	v_lshl_add_u64 v[52:53], v[158:159], 0, v[52:53]
	s_waitcnt vmcnt(7)
	v_mov_b32_e32 v52, v228
	v_mov_b32_e32 v53, v229
	v_mov_b32_e32 v54, v230
	v_mov_b32_e32 v55, v231
	v_mov_b32_e32 v56, v53
	v_mov_b32_e32 v57, v54
	v_mov_b32_e32 v53, v55
	v_pk_add_f32 v[52:53], v[56:57], v[52:53]
	s_nop 0
	v_add_f32_e32 v51, v52, v53
	ds_bpermute_b32 v52, v131, v51
	s_waitcnt lgkmcnt(0)
	v_add_f32_e32 v51, v51, v52
	ds_bpermute_b32 v52, v135, v51
	s_waitcnt lgkmcnt(0)
	v_add_f32_e32 v51, v51, v52
	v_fmamk_f32 v51, v51, 0x3a800000, v195
	v_mul_f32_e32 v52, 0x4b800000, v51
	v_cmp_gt_f32_e32 vcc, s68, v51
	s_nop 1
	v_cndmask_b32_e32 v51, v51, v52, vcc
	v_rsq_f32_e32 v51, v51
	s_nop 0
	v_mul_f32_e32 v52, 0x45800000, v51
	v_cndmask_b32_e32 v52, v51, v52, vcc
	s_and_saveexec_b64 s[30:31], s[8:9]
	ds_write_b32 v171, v52 offset:320
	s_or_b64 exec, exec, s[30:31]
	s_mov_b64 s[30:31], 0

; #define LAS __attribute__((address_space(3)))
; __device__ __forceinline__ unsigned pk_bf16(float lo, float hi) { const f32x2 v = {lo, hi}; const bf16x2_t b = __builtin_convertvector(v, bf16x2_t); return __builtin_bit_cast(unsigned, b); }
; __device__ __forceinline__ float row_rstd(const float* ssq, int row, int fq) {
;     const f32x4 s = *(const f32x4*)(ssq + (size_t)row * 16 + 4 * fq);
;     float t = (s[0] + s[1]) + (s[2] + s[3]);
;     t += __shfl_xor(t, 16); t += __shfl_xor(t, 32);
;     return rsqrtf(t * (1.0f / DM) + EPS);
; }
; __device__ __forceinline__ bool rc_hit(LAS float* rc, const int want, const int wave) { return __builtin_amdgcn_readfirstlane(*(volatile LAS int*)((LAS int*)(rc + 1024) + wave)) == want; }
; __device__ __forceinline__ float rc_get(LAS float* rc, const bool hit, const float* ssq, const int row, const int wave, const int slot, const int fr, const int fq) {
;     LAS float* e = rc + wave * 128 + slot * 16 + fr;
;     if (hit) return *e;
;     const float r = row_rstd(ssq, row, fq); if (fq == 0) *e = r; return r;
;     __device__ __forceinline__ void operator()(const f32x4 (&acc)[2][2][4][2], const pg8::Unit& u, int wr, int wc, int fr, int fq) const {
;     ...
;                 const int row = row0 + ai * 128 + m * 16; const float rs = rc_get(rc, rchit, ssq, row, rcw, ai * 4 + m, fr, fq);
;                 float h[8];
;                 const float c1 = rs * -1.4426950408889634f, rs2 = rs * rs;
; #pragma unroll
;                 for (int n = 0; n < 2; ++n)
; #pragma unroll
;                     for (int j = 0; j < 4; j += 2) { const f32x2 ag = {acc[ai][0][m][n][j], acc[ai][0][m][n][j + 1]}, au = {acc[ai][1][m][n][j], acc[ai][1][m][n][j + 1]};
;                         const f32x2 t = ag * c1; f32x2 e; e.x = __builtin_amdgcn_exp2f(t.x); e.y = __builtin_amdgcn_exp2f(t.y);
;                         const f32x2 d = e + 1.0f; f32x2 r; r.x = __builtin_amdgcn_rcpf(d.x); r.y = __builtin_amdgcn_rcpf(d.y);
;                         const f32x2 hh = (ag * au) * (r * rs2); h[n * 4 + j] = hh.x; h[n * 4 + j + 1] = hh.y; }
;                 u32x4 w; w.x = pk_bf16(h[0], h[1]); w.y = pk_bf16(h[2], h[3]); w.z = pk_bf16(h[4], h[5]); w.w = pk_bf16(h[6], h[7]);
;                 __builtin_nontemporal_store(w, (u32x4*)(H + (size_t)row * DFF + col0));
.LBB0_1803:
	s_waitcnt lgkmcnt(0)
	v_mul_f32_e32 v54, 0xbfb8aa3b, v52
	v_pk_mul_f32 v[56:57], v[46:47], v[54:55] op_sel_hi:[1,0]
	v_mul_f32_e32 v52, v52, v52
	v_exp_f32_e32 v56, v56
	v_exp_f32_e32 v57, v57
	v_pk_mul_f32 v[42:43], v[46:47], v[42:43]
	v_pk_mul_f32 v[44:45], v[48:49], v[44:45]
	v_pk_mul_f32 v[40:41], v[36:37], v[40:41]
	v_pk_add_f32 v[56:57], v[56:57], 1.0 op_sel_hi:[1,0]
	s_mov_b64 s[30:31], -1
	v_rcp_f32_e32 v56, v56
	v_rcp_f32_e32 v57, v57
	s_and_b64 vcc, exec, s[12:13]
	v_pk_mul_f32 v[46:47], v[52:53], v[56:57] op_sel_hi:[0,1]
	v_pk_mul_f32 v[42:43], v[42:43], v[46:47]
	v_pk_mul_f32 v[46:47], v[48:49], v[54:55] op_sel_hi:[1,0]
	s_nop 0
	v_exp_f32_e32 v46, v46
	v_exp_f32_e32 v47, v47
	s_nop 0
	v_pk_add_f32 v[46:47], v[46:47], 1.0 op_sel_hi:[1,0]
	s_nop 0
	v_rcp_f32_e32 v46, v46
	v_rcp_f32_e32 v47, v47
	s_nop 0
	v_pk_mul_f32 v[46:47], v[52:53], v[46:47] op_sel_hi:[0,1]
	v_pk_mul_f32 v[44:45], v[44:45], v[46:47]
	v_pk_mul_f32 v[46:47], v[34:35], v[54:55] op_sel_hi:[1,0]
	v_pk_mul_f32 v[34:35], v[34:35], v[38:39]
	v_exp_f32_e32 v46, v46
	v_exp_f32_e32 v47, v47
	s_nop 0
	v_pk_add_f32 v[46:47], v[46:47], 1.0 op_sel_hi:[1,0]
	s_nop 0
	v_rcp_f32_e32 v46, v46
	v_rcp_f32_e32 v47, v47
	s_nop 0
	v_pk_mul_f32 v[38:39], v[52:53], v[46:47] op_sel_hi:[0,1]
	v_pk_mul_f32 v[38:39], v[34:35], v[38:39]
	v_pk_mul_f32 v[34:35], v[36:37], v[54:55] op_sel_hi:[1,0]
	v_cvt_pk_bf16_f32 v36, v38, v39
	v_exp_f32_e32 v34, v34
	v_exp_f32_e32 v35, v35
	v_mov_b64_e32 v[38:39], s[16:17]
	v_mad_i64_i32 v[38:39], s[4:5], v50, s87, v[38:39]
	v_pk_add_f32 v[34:35], v[34:35], 1.0 op_sel_hi:[1,0]
	v_lshl_add_u64 v[38:39], v[164:165], 1, v[38:39]
	v_rcp_f32_e32 v34, v34
	v_rcp_f32_e32 v35, v35
	s_nop 0
	v_pk_mul_f32 v[34:35], v[52:53], v[34:35] op_sel_hi:[0,1]
	v_pk_mul_f32 v[40:41], v[40:41], v[34:35]
	v_cvt_pk_bf16_f32 v34, v42, v43
	v_cvt_pk_bf16_f32 v35, v44, v45
	v_cvt_pk_bf16_f32 v37, v40, v41
	global_store_dwordx4 v[38:39], v[34:37], off nt
	s_nop 1
	v_add_u32_e32 v34, 0xa0, v166
	v_ashrrev_i32_e32 v35, 31, v34
	s_cbranch_vccnz .LBB0_1807
	v_lshlrev_b64 v[36:37], 6, v[34:35]
	v_lshl_add_u64 v[36:37], v[158:159], 0, v[36:37]
	s_waitcnt vmcnt(7)
	v_mov_b32_e32 v36, v232
	v_mov_b32_e32 v37, v233
	v_mov_b32_e32 v38, v234
	v_mov_b32_e32 v39, v235
	v_mov_b32_e32 v40, v37
	v_mov_b32_e32 v41, v38
	v_mov_b32_e32 v37, v39
	v_pk_add_f32 v[36:37], v[40:41], v[36:37]
	s_nop 0
	v_add_f32_e32 v35, v36, v37
	ds_bpermute_b32 v36, v131, v35
	s_waitcnt lgkmcnt(0)
	v_add_f32_e32 v35, v35, v36
	ds_bpermute_b32 v36, v135, v35
	s_waitcnt lgkmcnt(0)
	v_add_f32_e32 v35, v35, v36
	v_fmamk_f32 v35, v35, 0x3a800000, v195
	v_mul_f32_e32 v36, 0x4b800000, v35
	v_cmp_gt_f32_e32 vcc, s68, v35
	s_nop 1
	v_cndmask_b32_e32 v35, v35, v36, vcc
	v_rsq_f32_e32 v35, v35
	s_nop 0
	v_mul_f32_e32 v36, 0x45800000, v35
	v_cndmask_b32_e32 v36, v35, v36, vcc
	s_and_saveexec_b64 s[30:31], s[8:9]
	ds_write_b32 v171, v36 offset:384
	s_or_b64 exec, exec, s[30:31]
	s_mov_b64 s[30:31], 0

; #define LAS __attribute__((address_space(3)))
; __device__ __forceinline__ unsigned pk_bf16(float lo, float hi) { const f32x2 v = {lo, hi}; const bf16x2_t b = __builtin_convertvector(v, bf16x2_t); return __builtin_bit_cast(unsigned, b); }
; __device__ __forceinline__ float row_rstd(const float* ssq, int row, int fq) {
;     const f32x4 s = *(const f32x4*)(ssq + (size_t)row * 16 + 4 * fq);
;     float t = (s[0] + s[1]) + (s[2] + s[3]);
;     t += __shfl_xor(t, 16); t += __shfl_xor(t, 32);
;     return rsqrtf(t * (1.0f / DM) + EPS);
; }
; __device__ __forceinline__ bool rc_hit(LAS float* rc, const int want, const int wave) { return __builtin_amdgcn_readfirstlane(*(volatile LAS int*)((LAS int*)(rc + 1024) + wave)) == want; }
; __device__ __forceinline__ float rc_get(LAS float* rc, const bool hit, const float* ssq, const int row, const int wave, const int slot, const int fr, const int fq) {
;     LAS float* e = rc + wave * 128 + slot * 16 + fr;
;     if (hit) return *e;
;     const float r = row_rstd(ssq, row, fq); if (fq == 0) *e = r; return r;
;     __device__ __forceinline__ void operator()(const f32x4 (&acc)[2][2][4][2], const pg8::Unit& u, int wr, int wc, int fr, int fq) const {
;     ...
;                 const int row = row0 + ai * 128 + m * 16; const float rs = rc_get(rc, rchit, ssq, row, rcw, ai * 4 + m, fr, fq);
;                 float h[8];
;                 const float c1 = rs * -1.4426950408889634f, rs2 = rs * rs;
; #pragma unroll
;                 for (int n = 0; n < 2; ++n)
; #pragma unroll
;                     for (int j = 0; j < 4; j += 2) { const f32x2 ag = {acc[ai][0][m][n][j], acc[ai][0][m][n][j + 1]}, au = {acc[ai][1][m][n][j], acc[ai][1][m][n][j + 1]};
;                         const f32x2 t = ag * c1; f32x2 e; e.x = __builtin_amdgcn_exp2f(t.x); e.y = __builtin_amdgcn_exp2f(t.y);
;                         const f32x2 d = e + 1.0f; f32x2 r; r.x = __builtin_amdgcn_rcpf(d.x); r.y = __builtin_amdgcn_rcpf(d.y);
;                         const f32x2 hh = (ag * au) * (r * rs2); h[n * 4 + j] = hh.x; h[n * 4 + j + 1] = hh.y; }
;                 u32x4 w; w.x = pk_bf16(h[0], h[1]); w.y = pk_bf16(h[2], h[3]); w.z = pk_bf16(h[4], h[5]); w.w = pk_bf16(h[6], h[7]);
;                 __builtin_nontemporal_store(w, (u32x4*)(H + (size_t)row * DFF + col0));
.LBB0_1809:
	s_waitcnt lgkmcnt(0)
	v_mul_f32_e32 v38, 0xbfb8aa3b, v36
	v_pk_mul_f32 v[40:41], v[30:31], v[38:39] op_sel_hi:[1,0]
	v_mul_f32_e32 v36, v36, v36
	v_exp_f32_e32 v40, v40
	v_exp_f32_e32 v41, v41
	v_pk_mul_f32 v[26:27], v[30:31], v[26:27]
	v_pk_mul_f32 v[28:29], v[32:33], v[28:29]
	v_pk_mul_f32 v[24:25], v[20:21], v[24:25]
	v_pk_add_f32 v[40:41], v[40:41], 1.0 op_sel_hi:[1,0]
	s_mov_b64 s[30:31], -1
	v_rcp_f32_e32 v40, v40
	v_rcp_f32_e32 v41, v41
	s_and_b64 vcc, exec, s[12:13]
	v_pk_mul_f32 v[30:31], v[36:37], v[40:41] op_sel_hi:[0,1]
	v_pk_mul_f32 v[26:27], v[26:27], v[30:31]
	v_pk_mul_f32 v[30:31], v[32:33], v[38:39] op_sel_hi:[1,0]
	s_nop 0
	v_exp_f32_e32 v30, v30
	v_exp_f32_e32 v31, v31
	s_nop 0
	v_pk_add_f32 v[30:31], v[30:31], 1.0 op_sel_hi:[1,0]
	s_nop 0
	v_rcp_f32_e32 v30, v30
	v_rcp_f32_e32 v31, v31
	s_nop 0
	v_pk_mul_f32 v[30:31], v[36:37], v[30:31] op_sel_hi:[0,1]
	v_pk_mul_f32 v[28:29], v[28:29], v[30:31]
	v_pk_mul_f32 v[30:31], v[18:19], v[38:39] op_sel_hi:[1,0]
	v_pk_mul_f32 v[18:19], v[18:19], v[22:23]
	v_exp_f32_e32 v30, v30
	v_exp_f32_e32 v31, v31
	s_nop 0
	v_pk_add_f32 v[30:31], v[30:31], 1.0 op_sel_hi:[1,0]
	s_nop 0
	v_rcp_f32_e32 v30, v30
	v_rcp_f32_e32 v31, v31
	s_nop 0
	v_pk_mul_f32 v[22:23], v[36:37], v[30:31] op_sel_hi:[0,1]
	v_pk_mul_f32 v[22:23], v[18:19], v[22:23]
	v_pk_mul_f32 v[18:19], v[20:21], v[38:39] op_sel_hi:[1,0]
	v_cvt_pk_bf16_f32 v20, v22, v23
	v_exp_f32_e32 v18, v18
	v_exp_f32_e32 v19, v19
	v_mov_b64_e32 v[22:23], s[16:17]
	v_mad_i64_i32 v[22:23], s[4:5], v34, s87, v[22:23]
	v_pk_add_f32 v[18:19], v[18:19], 1.0 op_sel_hi:[1,0]
	v_lshl_add_u64 v[22:23], v[164:165], 1, v[22:23]
	v_rcp_f32_e32 v18, v18
	v_rcp_f32_e32 v19, v19
	s_nop 0
	v_pk_mul_f32 v[18:19], v[36:37], v[18:19] op_sel_hi:[0,1]
	v_pk_mul_f32 v[24:25], v[24:25], v[18:19]
	v_cvt_pk_bf16_f32 v18, v26, v27
	v_cvt_pk_bf16_f32 v19, v28, v29
	v_cvt_pk_bf16_f32 v21, v24, v25
	global_store_dwordx4 v[22:23], v[18:21], off nt
	s_nop 1
	v_add_u32_e32 v18, 0xb0, v166
	v_ashrrev_i32_e32 v19, 31, v18
	s_cbranch_vccnz .LBB0_1813
	v_lshlrev_b64 v[20:21], 6, v[18:19]
	v_lshl_add_u64 v[20:21], v[158:159], 0, v[20:21]
	s_waitcnt vmcnt(7)
	v_mov_b32_e32 v20, v236
	v_mov_b32_e32 v21, v237
	v_mov_b32_e32 v22, v238
	v_mov_b32_e32 v23, v239
	v_mov_b32_e32 v24, v21
	v_mov_b32_e32 v25, v22
	v_mov_b32_e32 v21, v23
	v_pk_add_f32 v[20:21], v[24:25], v[20:21]
	s_nop 0
	v_add_f32_e32 v19, v20, v21
	ds_bpermute_b32 v20, v131, v19
	s_waitcnt lgkmcnt(0)
	v_add_f32_e32 v19, v19, v20
	ds_bpermute_b32 v20, v135, v19
	s_waitcnt lgkmcnt(0)
	v_add_f32_e32 v19, v19, v20
	v_fmamk_f32 v19, v19, 0x3a800000, v195
	v_mul_f32_e32 v20, 0x4b800000, v19
	v_cmp_gt_f32_e32 vcc, s68, v19
	s_nop 1
	v_cndmask_b32_e32 v19, v19, v20, vcc
	v_rsq_f32_e32 v19, v19
	s_nop 0
	v_mul_f32_e32 v20, 0x45800000, v19
	v_cndmask_b32_e32 v20, v19, v20, vcc
	s_and_saveexec_b64 s[12:13], s[8:9]
	ds_write_b32 v171, v20 offset:448
	s_or_b64 exec, exec, s[12:13]
	s_mov_b64 s[30:31], 0
